# plus: SGU weight tile staged once per workgroup instead of once per unit
# speedup vs baseline: 1.0329x; 1.0013x over previous
.LBB0_215:
	s_cmp_lg_u32 s95, s94
	s_cbranch_scc1 .LBB0_218
	s_and_saveexec_b64 s[22:23], s[2:3]
	s_cbranch_execz .LBB0_218
	s_mov_b64 s[24:25], 0
	v_mov_b32_e32 v1, v194
	v_mov_b32_e32 v4, v151
